# masked attention tiles: LDS-DMA staged K/V with prefetch distance 2, nbr parity skip, straight-line bias reads, hoisted fragment reads
# speedup vs baseline: 1.0240x; 1.0141x over previous
; #define ATT_LAS __attribute__((address_space(3)))
; __device__ __forceinline__ int crow(int r, int hi) { return (r & 3) + 8 * (r >> 2) + 4 * hi; }
; __device__ __forceinline__ void attn_unit(int uv, const float* sink_l, const bf16_t* P, bf16_t* Y, ATT_LAS unsigned char* lds, const float* rpb_l, const float* qn_l, const float* kn_l) {
;     ...
;     if (a.mode != 0 && nlat > 0) {
;         u32x4 kreg, vreg;
;         { const size_t ro = (size_t)ATT_TROW(4) * PITCH; kreg = *(const u32x4*)(kg + ro); vreg = *(const u32x4*)(vg + ro); }
;         *(ATT_LAS u32x4*)(ATT_KBUF(0) + koff) = kreg; *(ATT_LAS u32x4*)(ATT_VBUF(0) + voff) = vreg;
;         __syncthreads();
;         const int qw = a.qpos0 + 32 * wid, qr = qw >> 6;
;         for (int t = 0; t < nlat; ++t) {
;             const int cur = t & 1, tl = a.t_lo + t;
;             if (t + 1 < nlat) { const size_t ro = (size_t)ATT_TROW(t + 5) * PITCH; kreg = *(const u32x4*)(kg + ro); vreg = *(const u32x4*)(vg + ro); }
;             bool need;
;             if (a.mode == 1) need = (tl * 64 + 63 >= qw - 128) && (tl * 64 <= qw + 31 + 128);
;             else { const int rs = clampi(qr - 4, 0, 120); need = (tl >= rs) && (tl < rs + 8); }
;     ...
;                 else { const int qc = 32 * (wid & 1) + r32, cs = clampi(qc - 8, 0, 48); const ATT_LAS float* trow = tbl + (tl - qr + 7) * 31 + 15 - qc;
; #pragma unroll
;                     for (int r = 0; r < 16; ++r) { const int kcl = crow(r, hi);
;                         const float b0 = trow[kcl], b1 = trow[kcl + 32];
;                         p0[r] = ((unsigned)(kcl - cs) < 16u) ? p0[r] + b0 : NEGF;
;                         p1[r] = ((unsigned)(kcl + 32 - cs) < 16u) ? p1[r] + b1 : NEGF; } }
.LBB0_644:
	s_xor_b64 s[2:3], s[24:25], -1
	s_cmp_gt_i32 s71, 0
	s_cselect_b64 s[0:1], -1, 0
	s_and_b64 s[0:1], s[4:5], s[0:1]
	s_andn2_b64 vcc, exec, s[0:1]
	s_waitcnt lgkmcnt(0)
	s_cbranch_vccnz .LBB0_536
	s_lshl_b32 s92, s93, 6
	s_add_i32 s84, s27, s92
	v_mad_i64_i32 v[112:113], s[0:1], s84, v215, v[198:199]
	v_mad_i64_i32 v[114:115], s[0:1], s84, v215, v[200:201]
	v_lshrrev_b32_e32 v116, 6, v192
	v_and_b32_e32 v117, 63, v192
	v_lshrrev_b32_e32 v118, 3, v117
	v_sub_u32_e32 v118, v118, v116
	v_mul_i32_i24_e32 v118, 0x8ff0, v118
	v_ashrrev_i32_e32 v119, 31, v118
	v_lshl_add_u64 v[112:113], v[118:119], 0, v[112:113]
	v_and_b32_e32 v118, 3, v116
	v_lshlrev_b32_e32 v118, 4, v118
	v_lshlrev_b32_e32 v119, 3, v116
	v_sub_u32_e32 v118, v118, v119
	v_bfe_u32 v119, v117, 3, 1
	v_bfe_u32 v204, v117, 4, 1
	v_bfe_u32 v205, v117, 5, 1
	v_add_u32_e32 v208, v119, v204
	v_lshl_add_u32 v208, v205, 1, v208
	v_lshl_add_u32 v118, v208, 1, v118
	v_lshrrev_b32_e32 v209, 2, v116
	v_sub_u32_e32 v209, v209, v119
	v_mul_i32_i24_e32 v118, 0x1200, v118
	v_lshl_add_u32 v118, v209, 6, v118
	v_ashrrev_i32_e32 v119, 31, v118
	v_lshl_add_u64 v[114:115], v[118:119], 0, v[114:115]
	v_readfirstlane_b32 s100, v116
	s_mov_b64 s[98:99], 0x48000
	s_lshl_b32 s100, s100, 10
	s_mov_b32 m0, s100
	s_nop 0
	global_load_lds_dwordx4 v[112:113], off
	s_add_i32 s101, s100, 0x6000
	s_mov_b32 m0, s101
	s_nop 0
	global_load_lds_dwordx4 v[114:115], off
	v_lshl_add_u64 v[112:113], v[112:113], 0, s[98:99]
	v_lshl_add_u64 v[114:115], v[114:115], 0, s[98:99]
	s_cmp_gt_i32 s71, 1
	s_cbranch_scc0 .Lmk_pa1
	s_add_i32 s101, s100, 0x2000
	s_mov_b32 m0, s101
	s_nop 0
	global_load_lds_dwordx4 v[112:113], off
	s_add_i32 s101, s100, 0x8000
	s_mov_b32 m0, s101
	s_nop 0
	global_load_lds_dwordx4 v[114:115], off
	v_lshl_add_u64 v[112:113], v[112:113], 0, s[98:99]
	v_lshl_add_u64 v[114:115], v[114:115], 0, s[98:99]
.Lmk_pa1:
	v_and_or_b32 v32, s28, 32, v223
	v_subrev_co_u32_e32 v32, vcc, 8, v32
	v_min_u32_e32 v32, 48, v32
	v_or_b32_e32 v33, 32, v219
	v_cndmask_b32_e64 v32, v32, 0, vcc
	v_or_b32_e32 v50, 17, v219
	v_sub_u32_e32 v33, v33, v32
	v_or_b32_e32 v51, 49, v219
	v_cmp_gt_u32_e64 s[68:69], 16, v33
	v_sub_u32_e32 v33, v50, v32
	v_or_b32_e32 v34, 1, v219
	v_cmp_gt_u32_e64 s[40:41], 16, v33
	v_sub_u32_e32 v33, v51, v32
	v_sub_u32_e32 v34, v34, v32
	v_cmp_gt_u32_e64 s[42:43], 16, v33
	v_or_b32_e32 v33, 18, v219
	v_cmp_gt_u32_e64 s[4:5], 16, v34
	v_or_b32_e32 v34, 50, v219
	v_sub_u32_e32 v33, v33, v32
	v_cmp_gt_u32_e64 s[44:45], 16, v33
	v_sub_u32_e32 v33, v34, v32
	v_cmp_gt_u32_e64 s[46:47], 16, v33
	v_or_b32_e32 v33, 19, v219
	v_or_b32_e32 v34, 51, v219
	v_sub_u32_e32 v33, v33, v32
	v_cmp_gt_u32_e64 s[48:49], 16, v33
	v_sub_u32_e32 v33, v34, v32
	v_cmp_gt_u32_e64 s[50:51], 16, v33
	v_or_b32_e32 v33, 24, v219
	v_or_b32_e32 v34, 56, v219
	v_sub_u32_e32 v33, v33, v32
	v_cmp_gt_u32_e64 s[52:53], 16, v33
	v_sub_u32_e32 v33, v34, v32
	s_add_i32 s85, s28, s26
	v_cmp_gt_u32_e64 s[54:55], 16, v33
	v_or_b32_e32 v33, 25, v219
	s_ashr_i32 s82, s85, 6
	v_or_b32_e32 v34, 57, v219
	v_sub_u32_e32 v33, v33, v32
	s_add_i32 s0, s82, -4
	v_cmp_gt_u32_e64 s[56:57], 16, v33
	v_sub_u32_e32 v33, v34, v32
	s_min_u32 s0, s0, 0x78
	v_cmp_gt_u32_e64 s[58:59], 16, v33
	v_or_b32_e32 v33, 26, v219
	s_cmp_gt_i32 s82, 3
	v_or_b32_e32 v34, 58, v219
	v_sub_u32_e32 v33, v33, v32
	s_cselect_b32 s79, s0, 0
	v_cmp_gt_u32_e64 s[60:61], 16, v33
	v_sub_u32_e32 v33, v34, v32
	v_or_b32_e32 v35, 33, v219
	v_or_b32_e32 v36, 2, v219
	v_or_b32_e32 v37, 34, v219
	v_or_b32_e32 v38, 3, v219
	v_or_b32_e32 v39, 35, v219
	v_or_b32_e32 v40, 8, v219
	v_or_b32_e32 v41, 40, v219
	v_or_b32_e32 v42, 9, v219
	v_or_b32_e32 v43, 41, v219
	v_or_b32_e32 v44, 10, v219
	v_or_b32_e32 v45, 42, v219
	v_or_b32_e32 v46, 11, v219
	v_or_b32_e32 v47, 43, v219
	v_or_b32_e32 v48, 16, v219
	v_or_b32_e32 v49, 48, v219
	s_add_i32 s33, s85, 0xffffff80
	s_add_i32 s91, s85, 0x9f
	s_add_i32 s6, s79, 8
	v_cmp_gt_u32_e64 s[62:63], 16, v33
	v_or_b32_e32 v33, 27, v219
	v_or_b32_e32 v34, 59, v219
	s_lshl_b64 s[66:67], s[72:73], 1
	v_readlane_b32 vcc_lo, v255, 29
	v_sub_u32_e32 v52, v219, v32
	v_sub_u32_e32 v35, v35, v32
	v_sub_u32_e32 v36, v36, v32
	v_sub_u32_e32 v37, v37, v32
	v_sub_u32_e32 v38, v38, v32
	v_sub_u32_e32 v39, v39, v32
	v_sub_u32_e32 v40, v40, v32
	v_sub_u32_e32 v41, v41, v32
	v_sub_u32_e32 v42, v42, v32
	v_sub_u32_e32 v43, v43, v32
	v_sub_u32_e32 v44, v44, v32
	v_sub_u32_e32 v45, v45, v32
	v_sub_u32_e32 v46, v46, v32
	v_sub_u32_e32 v47, v47, v32
	v_sub_u32_e32 v48, v48, v32
	v_sub_u32_e32 v49, v49, v32
	v_sub_u32_e32 v33, v33, v32
	v_sub_u32_e32 v32, v34, v32
	v_readlane_b32 vcc_hi, v255, 30
	s_add_u32 s86, vcc_lo, s66
	s_movk_i32 s83, 0x1200
	s_addc_u32 s87, vcc_hi, s67
	v_cmp_gt_u32_e64 s[66:67], 16, v32
	v_add_u32_e32 v32, s37, v227
	v_cmp_gt_u32_e64 s[64:65], 16, v33
	v_mad_i64_i32 v[32:33], s[96:97], v32, s83, 0
	v_mad_i64_i32 v[32:33], s[96:97], s84, v215, v[32:33]
	s_movk_i32 s72, 0x70
	v_and_or_b32 v32, v230, s72, v32
	s_mul_hi_i32 s72, s84, 0x1200
	s_mulk_i32 s84, 0x1200
	s_lshl_b64 s[80:81], s[80:81], 1
	s_add_u32 s80, s80, s84
	s_addc_u32 s81, s81, s72
	v_lshl_add_u64 v[120:121], s[86:87], 0, v[32:33]
	v_add3_u32 v34, s37, v226, v225
	v_mov_b64_e32 v[32:33], s[80:81]
	v_mad_i64_i32 v[32:33], s[80:81], v34, s83, v[32:33]
	v_add_lshl_u32 v196, v228, v229, 1
	v_lshl_add_u64 v[32:33], v[32:33], 0, v[196:197]
	v_lshl_add_u64 v[122:123], vcc, 0, v[32:33]
	v_add_u32_e32 v32, s85, v223
	s_mul_i32 s72, s93, 0x7c
	v_sub_u32_e32 v126, v219, v32
	v_lshl_add_u32 v32, v224, 4, s72
	v_lshlrev_b32_e32 v33, 2, v223
	v_sub_u32_e32 v32, v32, v33
	s_mulk_i32 s82, 0x7c
	v_subrev_u32_e32 v32, s82, v32
	s_and_b32 s72, s34, 0x80
	v_subrev_u32_e32 v32, s72, v32
	v_readlane_b32 s72, v255, 31
	v_add_u32_e32 v125, s35, v231
	s_mov_b32 s7, 0
	v_cmp_gt_u32_e64 s[0:1], 16, v52
	v_cmp_gt_u32_e64 s[8:9], 16, v35
	v_cmp_gt_u32_e64 s[10:11], 16, v36
	v_cmp_gt_u32_e64 s[12:13], 16, v37
	v_cmp_gt_u32_e64 s[14:15], 16, v38
	v_cmp_gt_u32_e64 s[16:17], 16, v39
	v_cmp_gt_u32_e64 s[18:19], 16, v40
	v_cmp_gt_u32_e64 s[20:21], 16, v41
	v_cmp_gt_u32_e64 s[22:23], 16, v42
	v_cmp_gt_u32_e64 s[24:25], 16, v43
	v_cmp_gt_u32_e64 s[26:27], 16, v44
	v_cmp_gt_u32_e64 s[28:29], 16, v45
	v_cmp_gt_u32_e64 s[30:31], 16, v46
	v_cmp_gt_u32_e64 s[94:95], 16, v47
	v_cmp_gt_u32_e64 s[76:77], 16, v48
	v_cmp_gt_u32_e64 s[38:39], 16, v49
	v_add_u32_e32 v127, s72, v32
	s_mov_b32 s32, 0
	s_cmp_gt_i32 s71, 1
	s_cbranch_scc0 .Lmk_p0
	s_waitcnt vmcnt(2)
	s_branch .Lmk_p1
; __device__ __forceinline__ void attn_unit(int uv, const float* sink_l, const bf16_t* P, bf16_t* Y, ATT_LAS unsigned char* lds, const float* rpb_l, const float* qn_l, const float* kn_l) {
;     ...
;         for (int t = 0; t < nlat; ++t) {
;             const int cur = t & 1, tl = a.t_lo + t;
;             if (t + 1 < nlat) { const size_t ro = (size_t)ATT_TROW(t + 5) * PITCH; kreg = *(const u32x4*)(kg + ro); vreg = *(const u32x4*)(vg + ro); }
;             bool need;
;             if (a.mode == 1) need = (tl * 64 + 63 >= qw - 128) && (tl * 64 <= qw + 31 + 128);
;             else { const int rs = clampi(qr - 4, 0, 120); need = (tl >= rs) && (tl < rs + 8); }
;             if (need) {
;                 const ATT_LAS unsigned char* Kb = ATT_KBUF(cur); const ATT_LAS unsigned char* Vb = ATT_VBUF(cur);
;                 f32x16 p0 = {}, p1 = {};
; #pragma unroll
;                 for (int d0 = 0; d0 < 4; ++d0) {
;                     const bf16x8 k0 = *(const ATT_LAS bf16x8*)(Kb + kfrag + d0 * 2048);
;                     const bf16x8 k1 = *(const ATT_LAS bf16x8*)(Kb + kfrag + d0 * 2048 + 512);
;                     p0 = __builtin_amdgcn_mfma_f32_32x32x16_bf16(k0, qf[d0], p0, 0, 0, 0);
;                     p1 = __builtin_amdgcn_mfma_f32_32x32x16_bf16(k1, qf[d0], p1, 0, 0, 0);
;                 }
;                 if (a.mode == 1) { const int dq = tl * 64 - (qw + r32);
; #pragma unroll
;                     for (int r = 0; r < 16; ++r) { const int d = dq + crow(r, hi); if (d > 128 || d < -128) p0[r] = NEGF; if (d + 32 > 128 || d + 32 < -128) p1[r] = NEGF; } }
;                 else { const int qc = 32 * (wid & 1) + r32, cs = clampi(qc - 8, 0, 48); const ATT_LAS float* trow = tbl + (tl - qr + 7) * 31 + 15 - qc;
; #pragma unroll
;                     for (int r = 0; r < 16; ++r) { const int kcl = crow(r, hi);
;                         const float b0 = trow[kcl], b1 = trow[kcl + 32];
;                         p0[r] = ((unsigned)(kcl - cs) < 16u) ? p0[r] + b0 : NEGF;
;                         p1[r] = ((unsigned)(kcl + 32 - cs) < 16u) ? p1[r] + b1 : NEGF; } }
;                 const float mt = rowmax32(p0, p1);
;                 if (__any(mt > m)) { const float mn = fmaxf(m, mt), alpha = __builtin_amdgcn_exp2f(m - mn); m = mn; lsum *= alpha;
; #pragma unroll
;                     for (int r = 0; r < 16; ++r) { o0[r] *= alpha; o1[r] *= alpha; } }
.Lmk_p0:
	s_waitcnt vmcnt(0)
.Lmk_p1:
	s_barrier
.Lmk_top:
	s_add_i32 s96, s7, 2
	s_cmp_lt_i32 s96, s71
	s_cselect_b64 s[82:83], -1, 0
	s_cbranch_scc0 .Lmk_nodma
	s_add_i32 s80, s32, 2
	s_cmp_ge_u32 s80, 3
	s_cselect_b32 s81, 3, 0
	s_sub_i32 s80, s80, s81
	s_lshl_b32 s81, s80, 13
	s_add_i32 s96, s81, 0x6000
	s_cmp_eq_u32 s80, 2
	s_cselect_b32 s80, 0xc000, s96
	s_add_i32 s81, s81, s100
	s_mov_b32 m0, s81
	s_nop 0
	global_load_lds_dwordx4 v[112:113], off
	s_add_i32 s80, s80, s100
	s_mov_b32 m0, s80
	s_nop 0
	global_load_lds_dwordx4 v[114:115], off
	v_lshl_add_u64 v[112:113], v[112:113], 0, s[98:99]
	v_lshl_add_u64 v[114:115], v[114:115], 0, s[98:99]
.Lmk_nodma:
	s_and_b64 vcc, exec, s[2:3]
	s_cbranch_vccz .Lmk_need_win
	s_add_i32 s72, s93, s7
	s_cmp_ge_i32 s72, s79
	s_cbranch_scc0 .Lmsk_tail
	s_cmp_lt_i32 s72, s6
	s_cbranch_scc0 .Lmsk_tail
	s_branch .LBB0_657
.Lmk_need_win:
	s_add_i32 s72, s92, 63
	s_cmp_ge_i32 s72, s33
	s_cbranch_scc0 .Lmsk_tail
	s_cmp_le_i32 s92, s91
	s_cbranch_scc0 .Lmsk_tail
.LBB0_657:
	s_lshl_b32 s86, s32, 13
	s_cmp_eq_u32 s32, 2
	s_cselect_b32 s87, 0x6000, s86
	v_add_u32_e32 v40, s86, v221
	v_add_u32_e32 v242, s87, v125
	ds_read_b128 v[128:131], v40
	ds_read_b128 v[132:135], v40 offset:512
	ds_read_b128 v[136:139], v40 offset:2048
	ds_read_b128 v[140:143], v40 offset:2560
	ds_read_b128 v[144:147], v40 offset:4096
	ds_read_b128 v[148:151], v40 offset:4608
	ds_read_b128 v[152:155], v40 offset:6144
	ds_read_b128 v[156:159], v40 offset:6656
	s_and_b64 vcc, exec, s[2:3]
	s_cbranch_vccz .Lmsk_win
	v_readfirstlane_b32 vcc_lo, v192
	s_nop 0
	s_bitcmp1_b32 vcc_lo, 6
	s_cbranch_scc1 .Lnb_odd
	ds_read2_b32 v[32:33], v127 offset1:1
	ds_read2_b32 v[34:35], v127 offset0:2 offset1:3
	ds_read2_b32 v[36:37], v127 offset0:8 offset1:9
	ds_read2_b32 v[38:39], v127 offset0:10 offset1:11
	ds_read2_b32 v[40:41], v127 offset0:16 offset1:17
	ds_read2_b32 v[42:43], v127 offset0:18 offset1:19
	ds_read2_b32 v[44:45], v127 offset0:24 offset1:25
	s_waitcnt lgkmcnt(14)
	v_mfma_f32_32x32x16_bf16 v[80:95], v[128:131], v[96:99], 0
	ds_read2_b32 v[46:47], v127 offset0:26 offset1:27
	s_waitcnt lgkmcnt(14)
	v_mfma_f32_32x32x16_bf16 v[48:63], v[132:135], v[96:99], 0
	ds_read2_b32 v[64:65], v127 offset0:32 offset1:33
	s_waitcnt lgkmcnt(14)
	v_mfma_f32_32x32x16_bf16 v[80:95], v[136:139], v[100:103], v[80:95]
	ds_read2_b32 v[66:67], v127 offset0:34 offset1:35
	s_waitcnt lgkmcnt(14)
	v_mfma_f32_32x32x16_bf16 v[48:63], v[140:143], v[100:103], v[48:63]
	ds_read_b64_tr_b16 v[160:161], v242 offset:24576
	s_waitcnt lgkmcnt(14)
	v_mfma_f32_32x32x16_bf16 v[80:95], v[144:147], v[104:107], v[80:95]
	ds_read_b64_tr_b16 v[162:163], v242 offset:25088
	s_waitcnt lgkmcnt(14)
	v_mfma_f32_32x32x16_bf16 v[48:63], v[148:151], v[104:107], v[48:63]
	ds_read_b64_tr_b16 v[176:177], v242 offset:28672
	s_waitcnt lgkmcnt(14)
	v_mfma_f32_32x32x16_bf16 v[80:95], v[152:155], v[108:111], v[80:95]
	ds_read_b64_tr_b16 v[178:179], v242 offset:29184
	s_waitcnt lgkmcnt(14)
	v_mfma_f32_32x32x16_bf16 v[48:63], v[156:159], v[108:111], v[48:63]
	ds_read_b64_tr_b16 v[164:165], v242 offset:25600
	s_waitcnt lgkmcnt(14)
	ds_read_b64_tr_b16 v[166:167], v242 offset:26112
	s_nop 5
	v_add_f32_e32 v32, v80, v32
	v_add_f32_e32 v33, v81, v33
	v_cndmask_b32_e64 v32, v216, v32, s[0:1]
	v_cndmask_b32_e64 v33, v216, v33, s[4:5]
	s_waitcnt lgkmcnt(14)
	ds_read_b64_tr_b16 v[180:181], v242 offset:29696
	v_add_f32_e32 v34, v82, v34
	v_add_f32_e32 v35, v83, v35
	v_cndmask_b32_e64 v34, v216, v34, s[10:11]
	v_cndmask_b32_e64 v35, v216, v35, s[14:15]
	s_waitcnt lgkmcnt(14)
	ds_read_b64_tr_b16 v[182:183], v242 offset:30208
	v_add_f32_e32 v36, v84, v36
	v_add_f32_e32 v37, v85, v37
	v_cndmask_b32_e64 v36, v216, v36, s[18:19]
	v_cndmask_b32_e64 v37, v216, v37, s[22:23]
	s_waitcnt lgkmcnt(14)
	ds_read_b64_tr_b16 v[168:169], v242 offset:26624
	v_add_f32_e32 v38, v86, v38
	v_add_f32_e32 v39, v87, v39
	v_cndmask_b32_e64 v38, v216, v38, s[26:27]
	v_cndmask_b32_e64 v39, v216, v39, s[30:31]
	s_waitcnt lgkmcnt(14)
	ds_read_b64_tr_b16 v[170:171], v242 offset:27136
	v_add_f32_e32 v40, v88, v40
	v_add_f32_e32 v41, v89, v41
	v_cndmask_b32_e64 v40, v216, v40, s[76:77]
	v_cndmask_b32_e64 v41, v216, v41, s[40:41]
	s_waitcnt lgkmcnt(14)
	ds_read_b64_tr_b16 v[184:185], v242 offset:30720
	v_add_f32_e32 v42, v90, v42
	v_add_f32_e32 v43, v91, v43
	v_cndmask_b32_e64 v42, v216, v42, s[44:45]
	v_cndmask_b32_e64 v43, v216, v43, s[48:49]
	s_waitcnt lgkmcnt(14)
	ds_read_b64_tr_b16 v[186:187], v242 offset:31232
	v_add_f32_e32 v44, v92, v44
	v_add_f32_e32 v45, v93, v45
	v_cndmask_b32_e64 v44, v216, v44, s[52:53]
	v_cndmask_b32_e64 v45, v216, v45, s[56:57]
	s_waitcnt lgkmcnt(14)
	v_add_f32_e32 v46, v94, v46
	v_add_f32_e32 v47, v95, v47
	v_cndmask_b32_e64 v46, v216, v46, s[60:61]
	v_cndmask_b32_e64 v47, v216, v47, s[64:65]
	s_waitcnt lgkmcnt(13)
	v_add_f32_e32 v64, v48, v64
	v_add_f32_e32 v65, v49, v65
	v_cndmask_b32_e64 v64, v216, v64, s[68:69]
	v_cndmask_b32_e64 v65, v216, v65, s[8:9]
	s_waitcnt lgkmcnt(12)
	v_add_f32_e32 v66, v50, v66
	v_add_f32_e32 v67, v51, v67
	v_cndmask_b32_e64 v66, v216, v66, s[12:13]
	v_cndmask_b32_e64 v67, v216, v67, s[16:17]
	v_max3_f32 v204, v32, v33, v34
	v_max3_f32 v205, v35, v36, v37
	v_max3_f32 v204, v204, v38, v39
	v_max3_f32 v205, v205, v40, v41
	v_max3_f32 v204, v204, v42, v43
	v_max3_f32 v205, v205, v44, v45
	v_max3_f32 v204, v204, v46, v47
	v_max3_f32 v205, v205, v64, v65
	v_max3_f32 v204, v204, v66, v67
	v_max_f32_e32 v204, v204, v205
	v_mov_b32_e32 v205, v204
	s_nop 1
	v_permlane32_swap_b32_e32 v204, v205
	v_max_f32_e32 v204, v204, v205
	v_cmp_gt_f32_e32 vcc, v204, v202
	s_cbranch_vccz .Lnb_even_norescale
	v_max_f32_e32 v205, v202, v204
	v_sub_f32_e32 v208, v202, v205
	v_exp_f32_e32 v208, v208
	v_mov_b32_e32 v202, v205
	v_pk_mul_f32 v[0:1], v[0:1], v[208:209] op_sel_hi:[1,0]
	v_pk_mul_f32 v[2:3], v[2:3], v[208:209] op_sel_hi:[1,0]
	v_pk_mul_f32 v[4:5], v[4:5], v[208:209] op_sel_hi:[1,0]
	v_pk_mul_f32 v[6:7], v[6:7], v[208:209] op_sel_hi:[1,0]
	v_pk_mul_f32 v[8:9], v[8:9], v[208:209] op_sel_hi:[1,0]
	v_pk_mul_f32 v[10:11], v[10:11], v[208:209] op_sel_hi:[1,0]
	v_pk_mul_f32 v[12:13], v[12:13], v[208:209] op_sel_hi:[1,0]
	v_pk_mul_f32 v[14:15], v[14:15], v[208:209] op_sel_hi:[1,0]
	v_pk_mul_f32 v[16:17], v[16:17], v[208:209] op_sel_hi:[1,0]
	v_pk_mul_f32 v[18:19], v[18:19], v[208:209] op_sel_hi:[1,0]
	v_pk_mul_f32 v[20:21], v[20:21], v[208:209] op_sel_hi:[1,0]
	v_pk_mul_f32 v[22:23], v[22:23], v[208:209] op_sel_hi:[1,0]
	v_pk_mul_f32 v[24:25], v[24:25], v[208:209] op_sel_hi:[1,0]
	v_pk_mul_f32 v[26:27], v[26:27], v[208:209] op_sel_hi:[1,0]
	v_pk_mul_f32 v[28:29], v[28:29], v[208:209] op_sel_hi:[1,0]
	v_pk_mul_f32 v[30:31], v[30:31], v[208:209] op_sel_hi:[1,0]
	v_mul_f32_e32 v124, v124, v208
; #define ATT_LAS __attribute__((address_space(3)))
; __device__ __forceinline__ void attn_unit(int uv, const float* sink_l, const bf16_t* P, bf16_t* Y, ATT_LAS unsigned char* lds, const float* rpb_l, const float* qn_l, const float* kn_l) {
;     ...
;                 else { const int qc = 32 * (wid & 1) + r32, cs = clampi(qc - 8, 0, 48); const ATT_LAS float* trow = tbl + (tl - qr + 7) * 31 + 15 - qc;
; #pragma unroll
;                     for (int r = 0; r < 16; ++r) { const int kcl = crow(r, hi);
;                         const float b0 = trow[kcl], b1 = trow[kcl + 32];
;                         p0[r] = ((unsigned)(kcl - cs) < 16u) ? p0[r] + b0 : NEGF;
;                         p1[r] = ((unsigned)(kcl + 32 - cs) < 16u) ? p1[r] + b1 : NEGF; } }
;                 const float mt = rowmax32(p0, p1);
;                 if (__any(mt > m)) { const float mn = fmaxf(m, mt), alpha = __builtin_amdgcn_exp2f(m - mn); m = mn; lsum *= alpha;
;     ...
;                 float sum = 0.f;
; #pragma unroll
;                 for (int r = 0; r < 16; ++r) { p0[r] = __builtin_amdgcn_exp2f(p0[r] - m); p1[r] = __builtin_amdgcn_exp2f(p1[r] - m); sum += p0[r] + p1[r]; }
;                 lsum += sum;
;                 u32x4 pw[4];
; #pragma unroll
;                 for (int j = 0; j < 4; ++j) { pw[0][j] = pk_bf16(p0[2 * j], p0[2 * j + 1]); pw[1][j] = pk_bf16(p0[8 + 2 * j], p0[8 + 2 * j + 1]);
;                                               pw[2][j] = pk_bf16(p1[2 * j], p1[2 * j + 1]); pw[3][j] = pk_bf16(p1[8 + 2 * j], p1[8 + 2 * j + 1]); }
;                 const ATT_LAS unsigned char* vb = Vb + vlane;
; #pragma unroll
;                 for (int s = 0; s < 4; ++s) {
;                     const bf16x8 pa = __builtin_bit_cast(bf16x8, pw[s]);
;                     { const s16x4 lo = vtr(vb + s * 1024), h4 = vtr(vb + s * 1024 + 512);
;                       const bf16x8 vf = (bf16x8){lo[0], lo[1], lo[2], lo[3], h4[0], h4[1], h4[2], h4[3]};
;                       o0 = __builtin_amdgcn_mfma_f32_32x32x16_bf16(vf, pa, o0, 0, 0, 0); }
;                     { const s16x4 lo = vtr(vb + 4096 + s * 1024), h4 = vtr(vb + 4096 + s * 1024 + 512);
;                       const bf16x8 vf = (bf16x8){lo[0], lo[1], lo[2], lo[3], h4[0], h4[1], h4[2], h4[3]};
;                       o1 = __builtin_amdgcn_mfma_f32_32x32x16_bf16(vf, pa, o1, 0, 0, 0); }
;                 }
.Lnb_even_norescale:
	v_sub_f32_e32 v32, v32, v202
	v_sub_f32_e32 v33, v33, v202
	v_sub_f32_e32 v34, v34, v202
	v_sub_f32_e32 v35, v35, v202
	v_sub_f32_e32 v36, v36, v202
	v_sub_f32_e32 v37, v37, v202
	v_sub_f32_e32 v38, v38, v202
	v_sub_f32_e32 v39, v39, v202
	v_sub_f32_e32 v40, v40, v202
	v_sub_f32_e32 v41, v41, v202
	v_sub_f32_e32 v42, v42, v202
	v_sub_f32_e32 v43, v43, v202
	v_sub_f32_e32 v44, v44, v202
	v_sub_f32_e32 v45, v45, v202
	v_sub_f32_e32 v46, v46, v202
	v_sub_f32_e32 v47, v47, v202
	v_sub_f32_e32 v64, v64, v202
	v_sub_f32_e32 v65, v65, v202
	v_sub_f32_e32 v66, v66, v202
	v_sub_f32_e32 v67, v67, v202
	v_exp_f32_e32 v32, v32
	v_exp_f32_e32 v33, v33
	v_exp_f32_e32 v34, v34
	v_exp_f32_e32 v35, v35
	v_exp_f32_e32 v36, v36
	v_exp_f32_e32 v37, v37
	v_exp_f32_e32 v38, v38
	v_exp_f32_e32 v39, v39
	v_exp_f32_e32 v40, v40
	v_exp_f32_e32 v41, v41
	v_exp_f32_e32 v42, v42
	v_exp_f32_e32 v43, v43
	v_exp_f32_e32 v44, v44
	v_exp_f32_e32 v45, v45
	v_exp_f32_e32 v46, v46
	v_exp_f32_e32 v47, v47
	v_exp_f32_e32 v64, v64
	v_exp_f32_e32 v65, v65
	v_exp_f32_e32 v66, v66
	v_exp_f32_e32 v67, v67
	v_add_f32_e32 v204, v32, v33
	v_add_f32_e32 v205, v34, v35
	v_add_f32_e32 v204, v204, v36
	v_add_f32_e32 v205, v205, v37
	v_add_f32_e32 v204, v204, v38
	v_add_f32_e32 v205, v205, v39
	v_add_f32_e32 v204, v204, v40
	v_add_f32_e32 v205, v205, v41
	v_add_f32_e32 v204, v204, v42
	v_add_f32_e32 v205, v205, v43
	v_add_f32_e32 v204, v204, v44
	v_add_f32_e32 v205, v205, v45
	v_add_f32_e32 v204, v204, v46
	v_add_f32_e32 v205, v205, v47
	v_add_f32_e32 v204, v204, v64
	v_add_f32_e32 v205, v205, v65
	v_add_f32_e32 v204, v204, v66
	v_add_f32_e32 v205, v205, v67
	v_add_f32_e32 v204, v204, v205
	v_add_f32_e32 v124, v124, v204
	v_cvt_pk_bf16_f32 v32, v32, v33
	v_cvt_pk_bf16_f32 v33, v34, v35
	v_cvt_pk_bf16_f32 v34, v36, v37
	v_cvt_pk_bf16_f32 v35, v38, v39
	v_cvt_pk_bf16_f32 v36, v40, v41
	v_cvt_pk_bf16_f32 v37, v42, v43
	v_cvt_pk_bf16_f32 v38, v44, v45
	v_cvt_pk_bf16_f32 v39, v46, v47
	v_cvt_pk_bf16_f32 v40, v64, v65
	v_cvt_pk_bf16_f32 v41, v66, v67
	v_mov_b32_e32 v42, 0
	v_mov_b32_e32 v43, 0
	s_nop 1
	s_waitcnt lgkmcnt(0)
	v_mfma_f32_32x32x16_bf16 v[0:15], v[160:163], v[32:35], v[0:15]
	v_mfma_f32_32x32x16_bf16 v[16:31], v[176:179], v[32:35], v[16:31]
	v_mfma_f32_32x32x16_bf16 v[0:15], v[164:167], v[36:39], v[0:15]
	v_mfma_f32_32x32x16_bf16 v[16:31], v[180:183], v[36:39], v[16:31]
	v_mfma_f32_32x32x16_bf16 v[0:15], v[168:171], v[40:43], v[0:15]
	v_mfma_f32_32x32x16_bf16 v[16:31], v[184:187], v[40:43], v[16:31]
	s_branch .Lmsk_tail
.Lnb_odd:
	ds_read2_b32 v[64:65], v127 offset0:32 offset1:33
	ds_read2_b32 v[66:67], v127 offset0:34 offset1:35
	ds_read2_b32 v[68:69], v127 offset0:40 offset1:41
	ds_read2_b32 v[70:71], v127 offset0:42 offset1:43
	ds_read2_b32 v[72:73], v127 offset0:48 offset1:49
	ds_read2_b32 v[74:75], v127 offset0:50 offset1:51
	ds_read2_b32 v[76:77], v127 offset0:56 offset1:57
	s_waitcnt lgkmcnt(14)
	v_mfma_f32_32x32x16_bf16 v[80:95], v[128:131], v[96:99], 0
	ds_read2_b32 v[78:79], v127 offset0:58 offset1:59
	s_waitcnt lgkmcnt(14)
	v_mfma_f32_32x32x16_bf16 v[48:63], v[132:135], v[96:99], 0
	ds_read2_b32 v[44:45], v127 offset0:24 offset1:25
	s_waitcnt lgkmcnt(14)
	v_mfma_f32_32x32x16_bf16 v[80:95], v[136:139], v[100:103], v[80:95]
	ds_read2_b32 v[46:47], v127 offset0:26 offset1:27
	s_waitcnt lgkmcnt(14)
	v_mfma_f32_32x32x16_bf16 v[48:63], v[140:143], v[100:103], v[48:63]
	ds_read_b64_tr_b16 v[164:165], v242 offset:25600
	s_waitcnt lgkmcnt(14)
	v_mfma_f32_32x32x16_bf16 v[80:95], v[144:147], v[104:107], v[80:95]
	ds_read_b64_tr_b16 v[166:167], v242 offset:26112
	s_waitcnt lgkmcnt(14)
	v_mfma_f32_32x32x16_bf16 v[48:63], v[148:151], v[104:107], v[48:63]
	ds_read_b64_tr_b16 v[180:181], v242 offset:29696
	s_waitcnt lgkmcnt(14)
	v_mfma_f32_32x32x16_bf16 v[80:95], v[152:155], v[108:111], v[80:95]
	ds_read_b64_tr_b16 v[182:183], v242 offset:30208
	s_waitcnt lgkmcnt(14)
	v_mfma_f32_32x32x16_bf16 v[48:63], v[156:159], v[108:111], v[48:63]
	ds_read_b64_tr_b16 v[168:169], v242 offset:26624
	s_waitcnt lgkmcnt(14)
	ds_read_b64_tr_b16 v[170:171], v242 offset:27136
	s_nop 7
	s_nop 0
	v_add_f32_e32 v64, v48, v64
	v_add_f32_e32 v65, v49, v65
	v_cndmask_b32_e64 v64, v216, v64, s[68:69]
	v_cndmask_b32_e64 v65, v216, v65, s[8:9]
	s_waitcnt lgkmcnt(14)
	ds_read_b64_tr_b16 v[184:185], v242 offset:30720
	v_add_f32_e32 v66, v50, v66
	v_add_f32_e32 v67, v51, v67
	v_cndmask_b32_e64 v66, v216, v66, s[12:13]
	v_cndmask_b32_e64 v67, v216, v67, s[16:17]
	s_waitcnt lgkmcnt(14)
	ds_read_b64_tr_b16 v[186:187], v242 offset:31232
	v_add_f32_e32 v68, v52, v68
	v_add_f32_e32 v69, v53, v69
	v_cndmask_b32_e64 v68, v216, v68, s[20:21]
	v_cndmask_b32_e64 v69, v216, v69, s[24:25]
	s_waitcnt lgkmcnt(14)
	ds_read_b64_tr_b16 v[172:173], v242 offset:27648
	v_add_f32_e32 v70, v54, v70
	v_add_f32_e32 v71, v55, v71
	v_cndmask_b32_e64 v70, v216, v70, s[28:29]
	v_cndmask_b32_e64 v71, v216, v71, s[94:95]
	s_waitcnt lgkmcnt(14)
	ds_read_b64_tr_b16 v[174:175], v242 offset:28160
	v_add_f32_e32 v72, v56, v72
	v_add_f32_e32 v73, v57, v73
	v_cndmask_b32_e64 v72, v216, v72, s[38:39]
	v_cndmask_b32_e64 v73, v216, v73, s[42:43]
	s_waitcnt lgkmcnt(14)
	ds_read_b64_tr_b16 v[188:189], v242 offset:31744
	v_add_f32_e32 v74, v58, v74
	v_add_f32_e32 v75, v59, v75
	v_cndmask_b32_e64 v74, v216, v74, s[46:47]
	v_cndmask_b32_e64 v75, v216, v75, s[50:51]
	s_waitcnt lgkmcnt(14)
	ds_read_b64_tr_b16 v[190:191], v242 offset:32256
	v_add_f32_e32 v76, v60, v76
	v_add_f32_e32 v77, v61, v77
	v_cndmask_b32_e64 v76, v216, v76, s[54:55]
	v_cndmask_b32_e64 v77, v216, v77, s[58:59]
	s_waitcnt lgkmcnt(14)
	v_add_f32_e32 v78, v62, v78
	v_add_f32_e32 v79, v63, v79
	v_cndmask_b32_e64 v78, v216, v78, s[62:63]
	v_cndmask_b32_e64 v79, v216, v79, s[66:67]
	s_waitcnt lgkmcnt(13)
	v_add_f32_e32 v44, v92, v44
	v_add_f32_e32 v45, v93, v45
	v_cndmask_b32_e64 v44, v216, v44, s[52:53]
	v_cndmask_b32_e64 v45, v216, v45, s[56:57]
	s_waitcnt lgkmcnt(12)
	v_add_f32_e32 v46, v94, v46
	v_add_f32_e32 v47, v95, v47
	v_cndmask_b32_e64 v46, v216, v46, s[60:61]
	v_cndmask_b32_e64 v47, v216, v47, s[64:65]
	v_max3_f32 v204, v44, v45, v46
	v_max3_f32 v205, v47, v64, v65
	v_max3_f32 v204, v204, v66, v67
	v_max3_f32 v205, v205, v68, v69
	v_max3_f32 v204, v204, v70, v71
	v_max3_f32 v205, v205, v72, v73
	v_max3_f32 v204, v204, v74, v75
	v_max3_f32 v205, v205, v76, v77
	v_max3_f32 v204, v204, v78, v79
	v_max_f32_e32 v204, v204, v205
	v_mov_b32_e32 v205, v204
	s_nop 1
	v_permlane32_swap_b32_e32 v204, v205
	v_max_f32_e32 v204, v204, v205
	v_cmp_gt_f32_e32 vcc, v204, v202
	s_cbranch_vccz .Lnb_odd_norescale
; #define ATT_LAS __attribute__((address_space(3)))
; __device__ __forceinline__ unsigned pk_bf16(float lo, float hi) { unsigned r; asm volatile("v_cvt_pk_bf16_f32 %0, %1, %2" : "=v"(r) : "v"(lo), "v"(hi)); return r; }
; __device__ __forceinline__ void attn_unit(int uv, const float* sink_l, const bf16_t* P, bf16_t* Y, ATT_LAS unsigned char* lds, const float* rpb_l, const float* qn_l, const float* kn_l) {
;     ...
;                 if (__any(mt > m)) { const float mn = fmaxf(m, mt), alpha = __builtin_amdgcn_exp2f(m - mn); m = mn; lsum *= alpha;
; #pragma unroll
;                     for (int r = 0; r < 16; ++r) { o0[r] *= alpha; o1[r] *= alpha; } }
;                 float sum = 0.f;
; #pragma unroll
;                 for (int r = 0; r < 16; ++r) { p0[r] = __builtin_amdgcn_exp2f(p0[r] - m); p1[r] = __builtin_amdgcn_exp2f(p1[r] - m); sum += p0[r] + p1[r]; }
;                 lsum += sum;
;                 u32x4 pw[4];
; #pragma unroll
;                 for (int j = 0; j < 4; ++j) { pw[0][j] = pk_bf16(p0[2 * j], p0[2 * j + 1]); pw[1][j] = pk_bf16(p0[8 + 2 * j], p0[8 + 2 * j + 1]);
;                                               pw[2][j] = pk_bf16(p1[2 * j], p1[2 * j + 1]); pw[3][j] = pk_bf16(p1[8 + 2 * j], p1[8 + 2 * j + 1]); }
;                 const ATT_LAS unsigned char* vb = Vb + vlane;
; #pragma unroll
;                 for (int s = 0; s < 4; ++s) {
;                     const bf16x8 pa = __builtin_bit_cast(bf16x8, pw[s]);
;                     { const s16x4 lo = vtr(vb + s * 1024), h4 = vtr(vb + s * 1024 + 512);
;                       const bf16x8 vf = (bf16x8){lo[0], lo[1], lo[2], lo[3], h4[0], h4[1], h4[2], h4[3]};
;                       o0 = __builtin_amdgcn_mfma_f32_32x32x16_bf16(vf, pa, o0, 0, 0, 0); }
;                     { const s16x4 lo = vtr(vb + 4096 + s * 1024), h4 = vtr(vb + 4096 + s * 1024 + 512);
;                       const bf16x8 vf = (bf16x8){lo[0], lo[1], lo[2], lo[3], h4[0], h4[1], h4[2], h4[3]};
;                       o1 = __builtin_amdgcn_mfma_f32_32x32x16_bf16(vf, pa, o1, 0, 0, 0); }
;                 }
	v_max_f32_e32 v205, v202, v204
	v_sub_f32_e32 v208, v202, v205
	v_exp_f32_e32 v208, v208
	v_mov_b32_e32 v202, v205
	v_pk_mul_f32 v[0:1], v[0:1], v[208:209] op_sel_hi:[1,0]
	v_pk_mul_f32 v[2:3], v[2:3], v[208:209] op_sel_hi:[1,0]
	v_pk_mul_f32 v[4:5], v[4:5], v[208:209] op_sel_hi:[1,0]
	v_pk_mul_f32 v[6:7], v[6:7], v[208:209] op_sel_hi:[1,0]
	v_pk_mul_f32 v[8:9], v[8:9], v[208:209] op_sel_hi:[1,0]
	v_pk_mul_f32 v[10:11], v[10:11], v[208:209] op_sel_hi:[1,0]
	v_pk_mul_f32 v[12:13], v[12:13], v[208:209] op_sel_hi:[1,0]
	v_pk_mul_f32 v[14:15], v[14:15], v[208:209] op_sel_hi:[1,0]
	v_pk_mul_f32 v[16:17], v[16:17], v[208:209] op_sel_hi:[1,0]
	v_pk_mul_f32 v[18:19], v[18:19], v[208:209] op_sel_hi:[1,0]
	v_pk_mul_f32 v[20:21], v[20:21], v[208:209] op_sel_hi:[1,0]
	v_pk_mul_f32 v[22:23], v[22:23], v[208:209] op_sel_hi:[1,0]
	v_pk_mul_f32 v[24:25], v[24:25], v[208:209] op_sel_hi:[1,0]
	v_pk_mul_f32 v[26:27], v[26:27], v[208:209] op_sel_hi:[1,0]
	v_pk_mul_f32 v[28:29], v[28:29], v[208:209] op_sel_hi:[1,0]
	v_pk_mul_f32 v[30:31], v[30:31], v[208:209] op_sel_hi:[1,0]
	v_mul_f32_e32 v124, v124, v208
.Lnb_odd_norescale:
	v_sub_f32_e32 v44, v44, v202
	v_sub_f32_e32 v45, v45, v202
	v_sub_f32_e32 v46, v46, v202
	v_sub_f32_e32 v47, v47, v202
	v_sub_f32_e32 v64, v64, v202
	v_sub_f32_e32 v65, v65, v202
	v_sub_f32_e32 v66, v66, v202
	v_sub_f32_e32 v67, v67, v202
	v_sub_f32_e32 v68, v68, v202
	v_sub_f32_e32 v69, v69, v202
	v_sub_f32_e32 v70, v70, v202
	v_sub_f32_e32 v71, v71, v202
	v_sub_f32_e32 v72, v72, v202
	v_sub_f32_e32 v73, v73, v202
	v_sub_f32_e32 v74, v74, v202
	v_sub_f32_e32 v75, v75, v202
	v_sub_f32_e32 v76, v76, v202
	v_sub_f32_e32 v77, v77, v202
	v_sub_f32_e32 v78, v78, v202
	v_sub_f32_e32 v79, v79, v202
	v_exp_f32_e32 v44, v44
	v_exp_f32_e32 v45, v45
	v_exp_f32_e32 v46, v46
	v_exp_f32_e32 v47, v47
	v_exp_f32_e32 v64, v64
	v_exp_f32_e32 v65, v65
	v_exp_f32_e32 v66, v66
	v_exp_f32_e32 v67, v67
	v_exp_f32_e32 v68, v68
	v_exp_f32_e32 v69, v69
	v_exp_f32_e32 v70, v70
	v_exp_f32_e32 v71, v71
	v_exp_f32_e32 v72, v72
	v_exp_f32_e32 v73, v73
	v_exp_f32_e32 v74, v74
	v_exp_f32_e32 v75, v75
	v_exp_f32_e32 v76, v76
	v_exp_f32_e32 v77, v77
	v_exp_f32_e32 v78, v78
	v_exp_f32_e32 v79, v79
	v_add_f32_e32 v204, v44, v45
	v_add_f32_e32 v205, v46, v47
	v_add_f32_e32 v204, v204, v64
	v_add_f32_e32 v205, v205, v65
	v_add_f32_e32 v204, v204, v66
	v_add_f32_e32 v205, v205, v67
	v_add_f32_e32 v204, v204, v68
	v_add_f32_e32 v205, v205, v69
	v_add_f32_e32 v204, v204, v70
	v_add_f32_e32 v205, v205, v71
	v_add_f32_e32 v204, v204, v72
	v_add_f32_e32 v205, v205, v73
	v_add_f32_e32 v204, v204, v74
	v_add_f32_e32 v205, v205, v75
	v_add_f32_e32 v204, v204, v76
	v_add_f32_e32 v205, v205, v77
	v_add_f32_e32 v204, v204, v78
	v_add_f32_e32 v205, v205, v79
	v_add_f32_e32 v204, v204, v205
	v_add_f32_e32 v124, v124, v204
	v_cvt_pk_bf16_f32 v38, v44, v45
	v_cvt_pk_bf16_f32 v39, v46, v47
	v_cvt_pk_bf16_f32 v40, v64, v65
	v_cvt_pk_bf16_f32 v41, v66, v67
	v_cvt_pk_bf16_f32 v42, v68, v69
	v_cvt_pk_bf16_f32 v43, v70, v71
	v_cvt_pk_bf16_f32 v44, v72, v73
	v_cvt_pk_bf16_f32 v45, v74, v75
	v_cvt_pk_bf16_f32 v46, v76, v77
	v_cvt_pk_bf16_f32 v47, v78, v79
	v_mov_b32_e32 v36, 0
	v_mov_b32_e32 v37, 0
	s_nop 1
	s_waitcnt lgkmcnt(0)
	v_mfma_f32_32x32x16_bf16 v[0:15], v[164:167], v[36:39], v[0:15]
	v_mfma_f32_32x32x16_bf16 v[16:31], v[180:183], v[36:39], v[16:31]
	v_mfma_f32_32x32x16_bf16 v[0:15], v[168:171], v[40:43], v[0:15]
	v_mfma_f32_32x32x16_bf16 v[16:31], v[184:187], v[40:43], v[16:31]
	v_mfma_f32_32x32x16_bf16 v[0:15], v[172:175], v[44:47], v[0:15]
	v_mfma_f32_32x32x16_bf16 v[16:31], v[188:191], v[44:47], v[16:31]
	s_branch .Lmsk_tail
; #define ATT_LAS __attribute__((address_space(3)))
; __device__ __forceinline__ int crow(int r, int hi) { return (r & 3) + 8 * (r >> 2) + 4 * hi; }
; __device__ __forceinline__ void attn_unit(int uv, const float* sink_l, const bf16_t* P, bf16_t* Y, ATT_LAS unsigned char* lds, const float* rpb_l, const float* qn_l, const float* kn_l) {
;     ...
;                 const ATT_LAS unsigned char* Kb = ATT_KBUF(cur); const ATT_LAS unsigned char* Vb = ATT_VBUF(cur);
;                 f32x16 p0 = {}, p1 = {};
; #pragma unroll
;                 for (int d0 = 0; d0 < 4; ++d0) {
;                     const bf16x8 k0 = *(const ATT_LAS bf16x8*)(Kb + kfrag + d0 * 2048);
;                     const bf16x8 k1 = *(const ATT_LAS bf16x8*)(Kb + kfrag + d0 * 2048 + 512);
;                     p0 = __builtin_amdgcn_mfma_f32_32x32x16_bf16(k0, qf[d0], p0, 0, 0, 0);
;                     p1 = __builtin_amdgcn_mfma_f32_32x32x16_bf16(k1, qf[d0], p1, 0, 0, 0);
;                 }
;                 if (a.mode == 1) { const int dq = tl * 64 - (qw + r32);
; #pragma unroll
;                     for (int r = 0; r < 16; ++r) { const int d = dq + crow(r, hi); if (d > 128 || d < -128) p0[r] = NEGF; if (d + 32 > 128 || d + 32 < -128) p1[r] = NEGF; } }
.Lmsk_win:
	ds_read_b64_tr_b16 v[160:161], v242 offset:24576
	ds_read_b64_tr_b16 v[162:163], v242 offset:25088
	ds_read_b64_tr_b16 v[176:177], v242 offset:28672
	ds_read_b64_tr_b16 v[178:179], v242 offset:29184
	ds_read_b64_tr_b16 v[164:165], v242 offset:25600
	ds_read_b64_tr_b16 v[166:167], v242 offset:26112
	ds_read_b64_tr_b16 v[180:181], v242 offset:29696
	s_waitcnt lgkmcnt(14)
	v_mfma_f32_32x32x16_bf16 v[80:95], v[128:131], v[96:99], 0
	ds_read_b64_tr_b16 v[182:183], v242 offset:30208
	s_waitcnt lgkmcnt(14)
	v_mfma_f32_32x32x16_bf16 v[48:63], v[132:135], v[96:99], 0
	ds_read_b64_tr_b16 v[168:169], v242 offset:26624
	s_waitcnt lgkmcnt(14)
	v_mfma_f32_32x32x16_bf16 v[80:95], v[136:139], v[100:103], v[80:95]
	ds_read_b64_tr_b16 v[170:171], v242 offset:27136
	s_waitcnt lgkmcnt(14)
	v_mfma_f32_32x32x16_bf16 v[48:63], v[140:143], v[100:103], v[48:63]
	ds_read_b64_tr_b16 v[184:185], v242 offset:30720
	s_waitcnt lgkmcnt(14)
	v_mfma_f32_32x32x16_bf16 v[80:95], v[144:147], v[104:107], v[80:95]
	ds_read_b64_tr_b16 v[186:187], v242 offset:31232
	s_waitcnt lgkmcnt(14)
	v_mfma_f32_32x32x16_bf16 v[48:63], v[148:151], v[104:107], v[48:63]
	ds_read_b64_tr_b16 v[172:173], v242 offset:27648
	s_waitcnt lgkmcnt(14)
	v_mfma_f32_32x32x16_bf16 v[80:95], v[152:155], v[108:111], v[80:95]
	ds_read_b64_tr_b16 v[174:175], v242 offset:28160
	s_waitcnt lgkmcnt(14)
	v_mfma_f32_32x32x16_bf16 v[48:63], v[156:159], v[108:111], v[48:63]
	ds_read_b64_tr_b16 v[188:189], v242 offset:31744
	s_waitcnt lgkmcnt(14)
	ds_read_b64_tr_b16 v[190:191], v242 offset:32256
	s_nop 7
	v_add_u32_e32 v79, s92, v126
	v_add_u32_e32 v32, 0xffffff7f, v79
	v_cmp_lt_u32_e32 vcc, s88, v32
	v_add_u32_e32 v33, 0xffffff9f, v79
	v_add_u32_e32 v34, 0xffffffa0, v79
	s_nop 1
	v_cndmask_b32_e32 v32, v216, v80, vcc
	v_cmp_lt_u32_e32 vcc, s88, v33
	v_add_u32_e32 v33, 0xffffff80, v79
	v_add_u32_e32 v35, 0xffffffa1, v79
	v_cndmask_b32_e32 v64, v216, v48, vcc
	v_cmp_lt_u32_e32 vcc, s88, v33
	v_add_u32_e32 v36, 0xffffffa2, v79
	v_add_u32_e32 v37, 0xffffffa7, v79
	v_cndmask_b32_e32 v33, v216, v81, vcc
	v_cmp_lt_u32_e32 vcc, s88, v34
	v_add_u32_e32 v34, 0xffffff81, v79
	v_add_u32_e32 v38, 0xffffffa8, v79
	v_cndmask_b32_e32 v65, v216, v49, vcc
	v_cmp_lt_u32_e32 vcc, s88, v34
	v_add_u32_e32 v39, 0xffffffa9, v79
	v_add_u32_e32 v40, 0xffffffaa, v79
	v_cndmask_b32_e32 v34, v216, v82, vcc
	v_cmp_lt_u32_e32 vcc, s88, v35
	v_add_u32_e32 v35, 0xffffff82, v79
	v_add_u32_e32 v41, 0xffffffaf, v79
	v_cndmask_b32_e32 v66, v216, v50, vcc
	v_cmp_lt_u32_e32 vcc, s88, v35
	v_add_u32_e32 v42, 0xffffffb0, v79
	v_add_u32_e32 v43, 0xffffffb1, v79
	v_cndmask_b32_e32 v35, v216, v83, vcc
	v_cmp_lt_u32_e32 vcc, s88, v36
	v_add_u32_e32 v36, 0xffffff87, v79
	v_add_u32_e32 v44, 0xffffffb2, v79
	v_cndmask_b32_e32 v67, v216, v51, vcc
	v_cmp_lt_u32_e32 vcc, s88, v36
	v_add_u32_e32 v45, 0xffffffb7, v79
	v_add_u32_e32 v46, 0xffffffb8, v79
	v_cndmask_b32_e32 v36, v216, v84, vcc
	v_cmp_lt_u32_e32 vcc, s88, v37
	v_add_u32_e32 v37, 0xffffff88, v79
	v_add_u32_e32 v47, 0xffffffb9, v79
	v_cndmask_b32_e32 v68, v216, v52, vcc
	v_cmp_lt_u32_e32 vcc, s88, v37
	v_add_u32_e32 v48, 0xffffffba, v79
	s_nop 0
	v_cndmask_b32_e32 v37, v216, v85, vcc
	v_cmp_lt_u32_e32 vcc, s88, v38
	v_add_u32_e32 v38, 0xffffff89, v79
	s_nop 0
	v_cndmask_b32_e32 v69, v216, v53, vcc
	v_cmp_lt_u32_e32 vcc, s88, v38
	s_nop 1
	v_cndmask_b32_e32 v38, v216, v86, vcc
	v_cmp_lt_u32_e32 vcc, s88, v39
	v_add_u32_e32 v39, 0xffffff8a, v79
	s_nop 0
	v_cndmask_b32_e32 v70, v216, v54, vcc
	v_cmp_lt_u32_e32 vcc, s88, v39
	s_nop 1
	v_cndmask_b32_e32 v39, v216, v87, vcc
	v_cmp_lt_u32_e32 vcc, s88, v40
	v_add_u32_e32 v40, 0xffffff8f, v79
	s_nop 0
	v_cndmask_b32_e32 v71, v216, v55, vcc
	v_cmp_lt_u32_e32 vcc, s88, v40
	s_nop 1
	v_cndmask_b32_e32 v40, v216, v88, vcc
	v_cmp_lt_u32_e32 vcc, s88, v41
	v_add_u32_e32 v41, 0xffffff90, v79
	s_nop 0
	v_cndmask_b32_e32 v72, v216, v56, vcc
	v_cmp_lt_u32_e32 vcc, s88, v41
	s_nop 1
	v_cndmask_b32_e32 v41, v216, v89, vcc
	v_cmp_lt_u32_e32 vcc, s88, v42
	v_add_u32_e32 v42, 0xffffff91, v79
	s_nop 0
	v_cndmask_b32_e32 v73, v216, v57, vcc
	v_cmp_lt_u32_e32 vcc, s88, v42
	s_nop 1
	v_cndmask_b32_e32 v42, v216, v90, vcc
	v_cmp_lt_u32_e32 vcc, s88, v43
	v_add_u32_e32 v43, 0xffffff92, v79
	s_nop 0
	v_cndmask_b32_e32 v74, v216, v58, vcc
	v_cmp_lt_u32_e32 vcc, s88, v43
	s_nop 1
	v_cndmask_b32_e32 v43, v216, v91, vcc
	v_cmp_lt_u32_e32 vcc, s88, v44
	v_add_u32_e32 v44, 0xffffff97, v79
	s_nop 0
	v_cndmask_b32_e32 v75, v216, v59, vcc
	v_cmp_lt_u32_e32 vcc, s88, v44
	s_nop 1
	v_cndmask_b32_e32 v44, v216, v92, vcc
	v_cmp_lt_u32_e32 vcc, s88, v45
	v_add_u32_e32 v45, 0xffffff98, v79
	s_nop 0
	v_cndmask_b32_e32 v76, v216, v60, vcc
	v_cmp_lt_u32_e32 vcc, s88, v45
	s_nop 1
	v_cndmask_b32_e32 v45, v216, v93, vcc
	v_cmp_lt_u32_e32 vcc, s88, v46
	v_add_u32_e32 v46, 0xffffff99, v79
	s_nop 0
	v_cndmask_b32_e32 v77, v216, v61, vcc
	v_cmp_lt_u32_e32 vcc, s88, v46
	s_nop 1
	v_cndmask_b32_e32 v46, v216, v94, vcc
	v_cmp_lt_u32_e32 vcc, s88, v47
	v_add_u32_e32 v47, 0xffffff9a, v79
	s_nop 0
	v_cndmask_b32_e32 v78, v216, v62, vcc
	v_cmp_lt_u32_e32 vcc, s88, v47
	s_nop 1
	v_cndmask_b32_e32 v47, v216, v95, vcc
	v_cmp_lt_u32_e32 vcc, s88, v48
	s_nop 1
	v_cndmask_b32_e32 v79, v216, v63, vcc

; #define ATT_LAS __attribute__((address_space(3)))
; __device__ __forceinline__ unsigned pk_bf16(float lo, float hi) { unsigned r; asm volatile("v_cvt_pk_bf16_f32 %0, %1, %2" : "=v"(r) : "v"(lo), "v"(hi)); return r; }
; __device__ __forceinline__ void attn_unit(int uv, const float* sink_l, const bf16_t* P, bf16_t* Y, ATT_LAS unsigned char* lds, const float* rpb_l, const float* qn_l, const float* kn_l) {
;     ...
;                 float sum = 0.f;
; #pragma unroll
;                 for (int r = 0; r < 16; ++r) { p0[r] = __builtin_amdgcn_exp2f(p0[r] - m); p1[r] = __builtin_amdgcn_exp2f(p1[r] - m); sum += p0[r] + p1[r]; }
;                 lsum += sum;
;                 u32x4 pw[4];
; #pragma unroll
;                 for (int j = 0; j < 4; ++j) { pw[0][j] = pk_bf16(p0[2 * j], p0[2 * j + 1]); pw[1][j] = pk_bf16(p0[8 + 2 * j], p0[8 + 2 * j + 1]);
;                                               pw[2][j] = pk_bf16(p1[2 * j], p1[2 * j + 1]); pw[3][j] = pk_bf16(p1[8 + 2 * j], p1[8 + 2 * j + 1]); }
;                 const ATT_LAS unsigned char* vb = Vb + vlane;
; #pragma unroll
;                 for (int s = 0; s < 4; ++s) {
;                     const bf16x8 pa = __builtin_bit_cast(bf16x8, pw[s]);
;                     { const s16x4 lo = vtr(vb + s * 1024), h4 = vtr(vb + s * 1024 + 512);
;                       const bf16x8 vf = (bf16x8){lo[0], lo[1], lo[2], lo[3], h4[0], h4[1], h4[2], h4[3]};
;                       o0 = __builtin_amdgcn_mfma_f32_32x32x16_bf16(vf, pa, o0, 0, 0, 0); }
;                     { const s16x4 lo = vtr(vb + 4096 + s * 1024), h4 = vtr(vb + 4096 + s * 1024 + 512);
;                       const bf16x8 vf = (bf16x8){lo[0], lo[1], lo[2], lo[3], h4[0], h4[1], h4[2], h4[3]};
;                       o1 = __builtin_amdgcn_mfma_f32_32x32x16_bf16(vf, pa, o1, 0, 0, 0); }
;                 }
;             }
;             if (t + 1 < nlat) { *(ATT_LAS u32x4*)(ATT_KBUF(cur ^ 1) + koff) = kreg; *(ATT_LAS u32x4*)(ATT_VBUF(cur ^ 1) + voff) = vreg; }
;             __syncthreads();
;         }
.LBB0_695:
	v_sub_f32_e32 v32, v32, v202
	v_exp_f32_e32 v80, v32
	v_sub_f32_e32 v32, v64, v202
	v_exp_f32_e32 v81, v32
	v_sub_f32_e32 v32, v33, v202
	v_sub_f32_e32 v33, v65, v202
	v_exp_f32_e32 v32, v32
	v_exp_f32_e32 v196, v33
	v_add_f32_e32 v33, v80, v81
	v_pk_add_f32 v[48:49], v[32:33], v[196:197]
	v_sub_f32_e32 v33, v34, v202
	v_sub_f32_e32 v34, v66, v202
	v_pk_add_f32 v[48:49], v[48:49], v[48:49] op_sel_hi:[0,1]
	v_exp_f32_e32 v33, v33
	v_exp_f32_e32 v82, v34
	v_sub_f32_e32 v34, v35, v202
	v_sub_f32_e32 v35, v67, v202
	v_exp_f32_e32 v34, v34
	v_exp_f32_e32 v48, v35
	v_add_f32_e32 v35, v33, v82
	v_cvt_pk_bf16_f32 v32, v80, v32
	v_pk_add_f32 v[50:51], v[34:35], v[48:49]
	v_sub_f32_e32 v35, v36, v202
	v_sub_f32_e32 v36, v68, v202
	v_exp_f32_e32 v49, v36
	v_sub_f32_e32 v36, v37, v202
	v_pk_add_f32 v[50:51], v[50:51], v[50:51] op_sel_hi:[0,1]
	v_exp_f32_e32 v35, v35
	v_exp_f32_e32 v52, v36
	v_sub_f32_e32 v36, v69, v202
	v_exp_f32_e32 v50, v36
	v_add_f32_e32 v53, v35, v49
	v_pk_add_f32 v[36:37], v[52:53], v[50:51]
	s_nop 0
	v_pk_add_f32 v[54:55], v[36:37], v[36:37] op_sel_hi:[0,1]
	v_sub_f32_e32 v36, v38, v202
	v_exp_f32_e32 v51, v36
	v_sub_f32_e32 v36, v70, v202
	v_exp_f32_e32 v53, v36
	v_sub_f32_e32 v36, v39, v202
	v_exp_f32_e32 v56, v36
	v_sub_f32_e32 v36, v71, v202
	v_exp_f32_e32 v54, v36
	v_add_f32_e32 v57, v51, v53
	v_pk_add_f32 v[36:37], v[56:57], v[54:55]
	s_nop 0
	v_pk_add_f32 v[38:39], v[36:37], v[36:37] op_sel_hi:[0,1]
	v_sub_f32_e32 v36, v40, v202
	v_exp_f32_e32 v55, v36
	v_sub_f32_e32 v36, v72, v202
	v_exp_f32_e32 v57, v36
	v_sub_f32_e32 v36, v41, v202
	v_sub_f32_e32 v37, v73, v202
	v_exp_f32_e32 v36, v36
	v_exp_f32_e32 v38, v37
	v_add_f32_e32 v37, v55, v57
	v_pk_add_f32 v[40:41], v[36:37], v[38:39]
	s_nop 0
	v_pk_add_f32 v[58:59], v[40:41], v[40:41] op_sel_hi:[0,1]
	v_sub_f32_e32 v37, v42, v202
	v_sub_f32_e32 v39, v74, v202
	v_sub_f32_e32 v40, v43, v202
	v_exp_f32_e32 v37, v37
	v_exp_f32_e32 v39, v39
	v_exp_f32_e32 v42, v40
	v_sub_f32_e32 v40, v75, v202
	v_exp_f32_e32 v58, v40
	v_add_f32_e32 v43, v37, v39
	v_cvt_pk_bf16_f32 v36, v55, v36
	v_pk_add_f32 v[40:41], v[42:43], v[58:59]
	s_nop 0
	v_pk_add_f32 v[60:61], v[40:41], v[40:41] op_sel_hi:[0,1]
	v_sub_f32_e32 v40, v44, v202
	v_exp_f32_e32 v43, v40
	v_sub_f32_e32 v40, v76, v202
	v_exp_f32_e32 v59, v40
	v_sub_f32_e32 v40, v45, v202
	v_exp_f32_e32 v62, v40
	v_sub_f32_e32 v40, v77, v202
	v_exp_f32_e32 v60, v40
	v_add_f32_e32 v63, v43, v59
	v_pk_add_f32 v[40:41], v[62:63], v[60:61]
	s_nop 0
	v_pk_add_f32 v[64:65], v[40:41], v[40:41] op_sel_hi:[0,1]
	v_sub_f32_e32 v40, v46, v202
	v_exp_f32_e32 v61, v40
	v_sub_f32_e32 v40, v78, v202
	v_exp_f32_e32 v63, v40
	v_sub_f32_e32 v40, v47, v202
	v_exp_f32_e32 v66, v40
	v_sub_f32_e32 v40, v79, v202
	v_exp_f32_e32 v64, v40
	v_cvt_pk_bf16_f32 v40, v81, v196
	v_cvt_pk_bf16_f32 v44, v57, v38
	v_cvt_pk_bf16_f32 v33, v33, v34
	v_cvt_pk_bf16_f32 v37, v37, v42
	v_cvt_pk_bf16_f32 v41, v82, v48
	v_cvt_pk_bf16_f32 v45, v39, v58
	v_cvt_pk_bf16_f32 v34, v35, v52
	v_cvt_pk_bf16_f32 v38, v43, v62
	v_cvt_pk_bf16_f32 v42, v49, v50
	v_cvt_pk_bf16_f32 v46, v59, v60
	v_cvt_pk_bf16_f32 v35, v51, v56
	v_cvt_pk_bf16_f32 v39, v61, v66
	v_cvt_pk_bf16_f32 v43, v53, v54
	v_cvt_pk_bf16_f32 v47, v63, v64
	s_waitcnt lgkmcnt(0)
	v_mfma_f32_32x32x16_bf16 v[0:15], v[160:163], v[32:35], v[0:15]
	v_mfma_f32_32x32x16_bf16 v[16:31], v[176:179], v[32:35], v[16:31]
	v_add_f32_e32 v67, v61, v63
	v_mfma_f32_32x32x16_bf16 v[0:15], v[164:167], v[36:39], v[0:15]
	v_mfma_f32_32x32x16_bf16 v[16:31], v[180:183], v[36:39], v[16:31]
	v_add_f32_e64 v68, v66, v64
	v_mfma_f32_32x32x16_bf16 v[0:15], v[168:171], v[40:43], v[0:15]
	v_mfma_f32_32x32x16_bf16 v[16:31], v[184:187], v[40:43], v[16:31]
	v_add_f32_e64 v69, v67, v65
	v_mfma_f32_32x32x16_bf16 v[0:15], v[172:175], v[44:47], v[0:15]
	v_mfma_f32_32x32x16_bf16 v[16:31], v[188:191], v[44:47], v[16:31]
	v_add_f32_e32 v68, v68, v69
	v_add_f32_e32 v124, v124, v68
.Lmsk_tail:
	s_add_i32 s92, s92, 64
	v_add_u32_e32 v127, 0x7c, v127
	s_add_i32 s7, s7, 1
	s_add_i32 s32, s32, 1
	s_cmp_eq_u32 s32, 3
	s_cselect_b32 s32, 0, s32
	s_and_b64 vcc, exec, s[82:83]
	s_cbranch_vccz .Lmk_w0
	s_waitcnt vmcnt(2)
	s_branch .Lmk_w1

; #define ATT_LAS __attribute__((address_space(3)))
; __device__ __forceinline__ void attn_unit(int uv, const float* sink_l, const bf16_t* P, bf16_t* Y, ATT_LAS unsigned char* lds, const float* rpb_l, const float* qn_l, const float* kn_l) {
;     ...
;             if (t + 1 < nlat) { *(ATT_LAS u32x4*)(ATT_KBUF(cur ^ 1) + koff) = kreg; *(ATT_LAS u32x4*)(ATT_VBUF(cur ^ 1) + voff) = vreg; }
;             __syncthreads();
;         }
.Lmk_w1:
	s_waitcnt lgkmcnt(0)
	s_barrier
	s_cmp_lt_i32 s7, s71
	s_cbranch_scc1 .Lmk_top
	s_branch .LBB0_535

; __global__ void __launch_bounds__(NTHREADS, 2) fwd_megakernel(Args A) {
	.amdhsa_kernel _Z14fwd_megakernel4Args
		.amdhsa_group_segment_fixed_size 0
		.amdhsa_private_segment_fixed_size 0
		.amdhsa_kernarg_size 448
		.amdhsa_user_sgpr_count 2
		.amdhsa_user_sgpr_dispatch_ptr 0
		.amdhsa_user_sgpr_queue_ptr 0
		.amdhsa_user_sgpr_kernarg_segment_ptr 1
		.amdhsa_user_sgpr_dispatch_id 0
		.amdhsa_user_sgpr_kernarg_preload_length 0
		.amdhsa_user_sgpr_kernarg_preload_offset 0
		.amdhsa_user_sgpr_private_segment_size 0
		.amdhsa_uses_dynamic_stack 0
		.amdhsa_enable_private_segment 0
		.amdhsa_system_sgpr_workgroup_id_x 1
		.amdhsa_system_sgpr_workgroup_id_y 0
		.amdhsa_system_sgpr_workgroup_id_z 0
		.amdhsa_system_sgpr_workgroup_info 0
		.amdhsa_system_vgpr_workitem_id 2
		.amdhsa_next_free_vgpr 256
		.amdhsa_next_free_sgpr 102
		.amdhsa_accum_offset 256
		.amdhsa_reserve_vcc 1
		.amdhsa_float_round_mode_32 0
		.amdhsa_float_round_mode_16_64 0
		.amdhsa_float_denorm_mode_32 3
		.amdhsa_float_denorm_mode_16_64 3
		.amdhsa_dx10_clamp 1
		.amdhsa_ieee_mode 1
		.amdhsa_fp16_overflow 0
		.amdhsa_tg_split 0
		.amdhsa_exception_fp_ieee_invalid_op 0
		.amdhsa_exception_fp_denorm_src 0
		.amdhsa_exception_fp_ieee_div_zero 0
		.amdhsa_exception_fp_ieee_overflow 0
		.amdhsa_exception_fp_ieee_underflow 0
		.amdhsa_exception_fp_ieee_inexact 0
		.amdhsa_exception_int_div_zero 0
	.end_amdhsa_kernel

; __global__ void __launch_bounds__(NTHREADS, 2) fwd_megakernel(Args A) {
amdhsa.kernels:
  - .agpr_count:     0
    .args:
      - .offset:         0
        .size:           192
        .value_kind:     by_value
      - .offset:         192
        .size:           4
        .value_kind:     hidden_block_count_x
      - .offset:         196
        .size:           4
        .value_kind:     hidden_block_count_y
      - .offset:         200
        .size:           4
        .value_kind:     hidden_block_count_z
      - .offset:         204
        .size:           2
        .value_kind:     hidden_group_size_x
      - .offset:         206
        .size:           2
        .value_kind:     hidden_group_size_y
      - .offset:         208
        .size:           2
        .value_kind:     hidden_group_size_z
      - .offset:         210
        .size:           2
        .value_kind:     hidden_remainder_x
      - .offset:         212
        .size:           2
        .value_kind:     hidden_remainder_y
      - .offset:         214
        .size:           2
        .value_kind:     hidden_remainder_z
      - .offset:         232
        .size:           8
        .value_kind:     hidden_global_offset_x
      - .offset:         240
        .size:           8
        .value_kind:     hidden_global_offset_y
      - .offset:         248
        .size:           8
        .value_kind:     hidden_global_offset_z
      - .offset:         256
        .size:           2
        .value_kind:     hidden_grid_dims
      - .offset:         280
        .size:           8
        .value_kind:     hidden_multigrid_sync_arg
      - .offset:         312
        .size:           4
        .value_kind:     hidden_dynamic_lds_size
    .group_segment_fixed_size: 0
    .kernarg_segment_align: 8
    .kernarg_segment_size: 448
    .language:       OpenCL C
    .language_version:
      - 2
      - 0
    .max_flat_workgroup_size: 512
    .name:           _Z14fwd_megakernel4Args
    .private_segment_fixed_size: 0
    .sgpr_count:     108
    .sgpr_spill_count: 37
    .symbol:         _Z14fwd_megakernel4Args.kd
    .uniform_work_group_size: 1
    .uses_dynamic_stack: false
    .vgpr_count:     256
    .vgpr_spill_count: 0
    .wavefront_size: 64
